# cache policy: in-proj epilogue stores non-temporal, so the 260 MB output stream does not evict the A/B panels from L2
# speedup vs baseline: 1.0040x; 1.0040x over previous
.LBB0_343:
	v_lshl_add_u32 v156, s53, 8, v135
	v_lshl_or_b32 v150, s52, 8, v154
	v_mov_b64_e32 v[152:153], s[22:23]
	v_ashrrev_i32_e32 v151, 31, v150
	v_mad_i64_i32 v[152:153], s[0:1], v156, s93, v[152:153]
	v_lshl_add_u64 v[152:153], v[150:151], 1, v[152:153]
	v_cmp_gt_i32_e32 vcc, s94, v150
	s_and_saveexec_b64 s[0:1], vcc
	s_cbranch_execz .LBB0_345
	v_cvt_pk_bf16_f32 v120, v120, v121
	v_cvt_pk_bf16_f32 v121, v122, v123
	v_cvt_pk_bf16_f32 v122, v124, v125
	v_cvt_pk_bf16_f32 v123, v126, v127
	global_store_dwordx4 v[152:153], v[120:123], off nt
.LBB0_345:
	s_or_b64 exec, exec, s[0:1]
	s_nop 0
	v_or_b32_e32 v120, 0x80, v150
	v_cmp_gt_i32_e64 s[0:1], s94, v120
	s_and_saveexec_b64 s[26:27], s[0:1]
	s_cbranch_execz .LBB0_347
	v_cvt_pk_bf16_f32 v116, v116, v117
	v_cvt_pk_bf16_f32 v117, v118, v119
	v_cvt_pk_bf16_f32 v118, v112, v113
	v_cvt_pk_bf16_f32 v119, v114, v115
	global_store_dwordx4 v[152:153], v[116:119], off offset:256 nt
.LBB0_347:
	s_or_b64 exec, exec, s[26:27]
	v_or_b32_e32 v114, 16, v156
	v_mov_b64_e32 v[112:113], s[22:23]
	v_mad_i64_i32 v[112:113], s[26:27], v114, s93, v[112:113]
	v_lshl_add_u64 v[112:113], v[150:151], 1, v[112:113]
	s_and_saveexec_b64 s[26:27], vcc
	s_cbranch_execz .LBB0_349
	v_cvt_pk_bf16_f32 v108, v108, v109
	v_cvt_pk_bf16_f32 v109, v110, v111
	v_cvt_pk_bf16_f32 v110, v104, v105
	v_cvt_pk_bf16_f32 v111, v106, v107
	global_store_dwordx4 v[112:113], v[108:111], off nt
.LBB0_349:
	s_or_b64 exec, exec, s[26:27]
	s_and_saveexec_b64 s[26:27], s[0:1]
	s_cbranch_execz .LBB0_351
	v_cvt_pk_bf16_f32 v100, v100, v101
	v_cvt_pk_bf16_f32 v101, v102, v103
	v_cvt_pk_bf16_f32 v102, v96, v97
	v_cvt_pk_bf16_f32 v103, v98, v99
	global_store_dwordx4 v[112:113], v[100:103], off offset:256 nt
.LBB0_351:
	s_or_b64 exec, exec, s[26:27]
	v_or_b32_e32 v98, 32, v156
	v_mov_b64_e32 v[96:97], s[22:23]
	v_mad_i64_i32 v[96:97], s[26:27], v98, s93, v[96:97]
	v_lshl_add_u64 v[96:97], v[150:151], 1, v[96:97]
	s_and_saveexec_b64 s[26:27], vcc
	s_cbranch_execz .LBB0_353
	v_cvt_pk_bf16_f32 v92, v92, v93
	v_cvt_pk_bf16_f32 v93, v94, v95
	v_cvt_pk_bf16_f32 v94, v88, v89
	v_cvt_pk_bf16_f32 v95, v90, v91
	global_store_dwordx4 v[96:97], v[92:95], off nt
.LBB0_353:
	s_or_b64 exec, exec, s[26:27]
	s_and_saveexec_b64 s[26:27], s[0:1]
	s_cbranch_execz .LBB0_355
	v_cvt_pk_bf16_f32 v84, v84, v85
	v_cvt_pk_bf16_f32 v85, v86, v87
	v_cvt_pk_bf16_f32 v86, v80, v81
	v_cvt_pk_bf16_f32 v87, v82, v83
	global_store_dwordx4 v[96:97], v[84:87], off offset:256 nt
.LBB0_355:
	s_or_b64 exec, exec, s[26:27]
	v_or_b32_e32 v82, 48, v156
	v_mov_b64_e32 v[80:81], s[22:23]
	v_mad_i64_i32 v[80:81], s[26:27], v82, s93, v[80:81]
	v_lshl_add_u64 v[80:81], v[150:151], 1, v[80:81]
	s_and_saveexec_b64 s[26:27], vcc
	s_cbranch_execz .LBB0_357
	v_cvt_pk_bf16_f32 v76, v76, v77
	v_cvt_pk_bf16_f32 v77, v78, v79
	v_cvt_pk_bf16_f32 v78, v72, v73
	v_cvt_pk_bf16_f32 v79, v74, v75
	global_store_dwordx4 v[80:81], v[76:79], off nt
.LBB0_357:
	s_or_b64 exec, exec, s[26:27]
	s_and_saveexec_b64 s[26:27], s[0:1]
	s_cbranch_execz .LBB0_359
	v_cvt_pk_bf16_f32 v68, v68, v69
	v_cvt_pk_bf16_f32 v69, v70, v71
	v_cvt_pk_bf16_f32 v70, v64, v65
	v_cvt_pk_bf16_f32 v71, v66, v67
	global_store_dwordx4 v[80:81], v[68:71], off offset:256 nt
.LBB0_359:
	s_or_b64 exec, exec, s[26:27]
	v_add_u32_e32 v66, 0x80, v156
	v_mov_b64_e32 v[64:65], s[22:23]
	v_mad_i64_i32 v[64:65], s[26:27], v66, s93, v[64:65]
	v_lshl_add_u64 v[64:65], v[150:151], 1, v[64:65]
	s_and_saveexec_b64 s[26:27], vcc
	s_cbranch_execz .LBB0_361
	v_cvt_pk_bf16_f32 v60, v60, v61
	v_cvt_pk_bf16_f32 v61, v62, v63
	v_cvt_pk_bf16_f32 v62, v56, v57
	v_cvt_pk_bf16_f32 v63, v58, v59
	global_store_dwordx4 v[64:65], v[60:63], off nt
.LBB0_361:
	s_or_b64 exec, exec, s[26:27]
	s_and_saveexec_b64 s[26:27], s[0:1]
	s_cbranch_execz .LBB0_363
	v_cvt_pk_bf16_f32 v52, v52, v53
	v_cvt_pk_bf16_f32 v53, v54, v55
	v_cvt_pk_bf16_f32 v54, v48, v49
	v_cvt_pk_bf16_f32 v55, v50, v51
	global_store_dwordx4 v[64:65], v[52:55], off offset:256 nt
.LBB0_363:
	s_or_b64 exec, exec, s[26:27]
	v_add_u32_e32 v50, 0x90, v156
	v_mov_b64_e32 v[48:49], s[22:23]
	v_mad_i64_i32 v[48:49], s[26:27], v50, s93, v[48:49]
	v_lshl_add_u64 v[48:49], v[150:151], 1, v[48:49]
	s_and_saveexec_b64 s[26:27], vcc
	s_cbranch_execz .LBB0_365
	v_cvt_pk_bf16_f32 v44, v44, v45
	v_cvt_pk_bf16_f32 v45, v46, v47
	v_cvt_pk_bf16_f32 v46, v40, v41
	v_cvt_pk_bf16_f32 v47, v42, v43
	global_store_dwordx4 v[48:49], v[44:47], off nt
.LBB0_365:
	s_or_b64 exec, exec, s[26:27]
	s_and_saveexec_b64 s[26:27], s[0:1]
	s_cbranch_execz .LBB0_367
	v_cvt_pk_bf16_f32 v36, v36, v37
	v_cvt_pk_bf16_f32 v37, v38, v39
	v_cvt_pk_bf16_f32 v38, v32, v33
	v_cvt_pk_bf16_f32 v39, v34, v35
	global_store_dwordx4 v[48:49], v[36:39], off offset:256 nt
.LBB0_367:
	s_or_b64 exec, exec, s[26:27]
	v_add_u32_e32 v34, 0xa0, v156
	v_mov_b64_e32 v[32:33], s[22:23]
	v_mad_i64_i32 v[32:33], s[26:27], v34, s93, v[32:33]
	v_lshl_add_u64 v[32:33], v[150:151], 1, v[32:33]
	s_and_saveexec_b64 s[26:27], vcc
	s_cbranch_execz .LBB0_369
	v_cvt_pk_bf16_f32 v28, v28, v29
	v_cvt_pk_bf16_f32 v29, v30, v31
	v_cvt_pk_bf16_f32 v30, v24, v25
	v_cvt_pk_bf16_f32 v31, v26, v27
	global_store_dwordx4 v[32:33], v[28:31], off nt
.LBB0_369:
	s_or_b64 exec, exec, s[26:27]
	s_and_saveexec_b64 s[26:27], s[0:1]
	s_cbranch_execz .LBB0_371
	v_cvt_pk_bf16_f32 v20, v20, v21
	v_cvt_pk_bf16_f32 v21, v22, v23
	v_cvt_pk_bf16_f32 v22, v16, v17
	v_cvt_pk_bf16_f32 v23, v18, v19
	global_store_dwordx4 v[32:33], v[20:23], off offset:256 nt

.LBB0_374:
	v_cvt_pk_bf16_f32 v12, v12, v13
	v_cvt_pk_bf16_f32 v13, v14, v15
	v_cvt_pk_bf16_f32 v14, v8, v9
	v_cvt_pk_bf16_f32 v15, v10, v11
	global_store_dwordx4 v[16:17], v[12:15], off nt
	s_or_b64 exec, exec, s[26:27]
	s_and_saveexec_b64 s[26:27], s[0:1]
	s_cbranch_execz .LBB0_373
.LBB0_375:
	v_cvt_pk_bf16_f32 v4, v4, v5
	v_cvt_pk_bf16_f32 v5, v6, v7
	v_cvt_pk_bf16_f32 v6, v0, v1
	v_cvt_pk_bf16_f32 v7, v2, v3
	global_store_dwordx4 v[16:17], v[4:7], off offset:256 nt
	s_or_b64 exec, exec, s[26:27]
	s_and_b64 vcc, exec, s[40:41]
	s_mov_b64 s[0:1], -1
	s_cbranch_vccnz .LBB0_326
